# folded-LN column-sum rows (ff1, and next layer w_in) moved from the fix-up phase into the mixers work queue as 256 tail items picked up by idle workgroups
# speedup vs baseline: 1.0152x; 1.0067x over previous
.LBB0_544:
	s_or_b64 exec, exec, s[10:11]
	s_waitcnt vmcnt(7)
	v_mov_b32_e32 v0, s53
	s_waitcnt lgkmcnt(0)
	s_barrier
	ds_read_b32 v0, v0
	s_waitcnt lgkmcnt(0)
	s_barrier
	v_readfirstlane_b32 s81, v0
	s_cmpk_gt_i32 s81, 0x405
	s_cbranch_scc1 .LBB0_779

.LBB0_732:
	s_cmpk_lt_i32 s81, 0x306
	s_cbranch_scc0 .Lrs_item
	s_mov_b64 s[12:13], s[0:1]
	s_add_i32 s4, s81, 0xfffffd7a
	s_add_i32 s10, s4, s75
	s_load_dwordx4 s[28:31], s[12:13], 0x10
	s_load_dwordx2 s[22:23], s[12:13], 0x40
	s_load_dwordx4 s[24:27], s[12:13], 0xc8
	s_ashr_i32 s11, s10, 31
	s_lshl_b64 s[10:11], s[10:11], 16
	s_waitcnt lgkmcnt(0)
	s_add_u32 s12, s28, s10
	s_waitcnt vmcnt(5)
	v_mov_b32_e32 v8, v236
	s_addc_u32 s13, s29, s11
	s_add_u32 s16, s30, s10
	v_ashrrev_i32_e32 v9, 31, v8
	s_addc_u32 s17, s31, s11
	v_lshlrev_b64 v[4:5], 4, v[8:9]
	s_waitcnt vmcnt(4)
	v_lshl_add_u64 v[12:13], s[12:13], 0, v[4:5]
	v_lshl_add_u64 v[10:11], s[16:17], 0, v[4:5]
	global_load_dwordx4 v[116:119], v[12:13], off nt
	global_load_dwordx4 v[120:123], v[10:11], off nt
	v_add_co_u32_e32 v200, vcc, 0x2000, v12
	s_nop 1
	v_addc_co_u32_e32 v201, vcc, 0, v13, vcc
	v_add_co_u32_e32 v202, vcc, 0x2000, v10
	s_nop 1
	v_addc_co_u32_e32 v203, vcc, 0, v11, vcc
	global_load_dwordx4 v[124:127], v[200:201], off nt
	global_load_dwordx4 v[128:131], v[202:203], off nt
	v_add_co_u32_e32 v200, vcc, 0x4000, v12
	s_nop 1
	v_addc_co_u32_e32 v201, vcc, 0, v13, vcc
	v_add_co_u32_e32 v202, vcc, 0x4000, v10
	s_nop 1
	v_addc_co_u32_e32 v203, vcc, 0, v11, vcc
	global_load_dwordx4 v[132:135], v[200:201], off nt
	global_load_dwordx4 v[136:139], v[202:203], off nt
	v_add_co_u32_e32 v200, vcc, 0x6000, v12
	s_nop 1
	v_addc_co_u32_e32 v201, vcc, 0, v13, vcc
	v_add_co_u32_e32 v202, vcc, 0x6000, v10
	s_nop 1
	v_addc_co_u32_e32 v203, vcc, 0, v11, vcc
	global_load_dwordx4 v[140:143], v[200:201], off nt
	global_load_dwordx4 v[144:147], v[202:203], off nt
	v_add_co_u32_e32 v200, vcc, 0x8000, v12
	s_nop 1
	v_addc_co_u32_e32 v201, vcc, 0, v13, vcc
	v_add_co_u32_e32 v202, vcc, 0x8000, v10
	s_nop 1
	v_addc_co_u32_e32 v203, vcc, 0, v11, vcc
	global_load_dwordx4 v[148:151], v[200:201], off nt
	global_load_dwordx4 v[152:155], v[202:203], off nt
	v_add_co_u32_e32 v200, vcc, 0xa000, v12
	s_nop 1
	v_addc_co_u32_e32 v201, vcc, 0, v13, vcc
	v_add_co_u32_e32 v202, vcc, 0xa000, v10
	s_nop 1
	v_addc_co_u32_e32 v203, vcc, 0, v11, vcc
	global_load_dwordx4 v[156:159], v[200:201], off nt
	global_load_dwordx4 v[160:163], v[202:203], off nt
	v_add_co_u32_e32 v200, vcc, 0xc000, v12
	s_nop 1
	v_addc_co_u32_e32 v201, vcc, 0, v13, vcc
	v_add_co_u32_e32 v202, vcc, 0xc000, v10
	s_nop 1
	v_addc_co_u32_e32 v203, vcc, 0, v11, vcc
	global_load_dwordx4 v[184:187], v[200:201], off nt
	global_load_dwordx4 v[188:191], v[202:203], off nt
	v_add_co_u32_e32 v200, vcc, 0xe000, v12
	s_nop 1
	v_addc_co_u32_e32 v201, vcc, 0, v13, vcc
	v_add_co_u32_e32 v202, vcc, 0xe000, v10
	s_nop 1
	v_addc_co_u32_e32 v203, vcc, 0, v11, vcc
	global_load_dwordx4 v[192:195], v[200:201], off nt
	global_load_dwordx4 v[196:199], v[202:203], off nt
	s_add_u32 s10, s24, s10
	s_addc_u32 s11, s25, s11
	v_lshlrev_b32_e32 v14, 4, v8
	s_add_u32 s24, s10, 0x41a6000
	s_waitcnt vmcnt(19)
	v_ashrrev_i32_e32 v16, 5, v8
	v_and_b32_e32 v15, 0x1f0, v14
	s_addc_u32 s25, s11, 0
	s_waitcnt vmcnt(16)
	v_mul_lo_u32 v17, v16, s72
	v_add_u32_e32 v14, 0, v15
	v_readlane_b32 s12, v255, 52
	s_add_u32 s28, s10, 0x51a6000
	v_readfirstlane_b32 s16, v8
	v_add_u32_e32 v15, s12, v15
	v_add_u32_e32 v18, v14, v17
	s_addc_u32 s29, s11, 0
	v_cmp_lt_i32_e32 vcc, 0, v16
	v_add_u32_e32 v17, v15, v17
	s_waitcnt vmcnt(15)
	ds_write_b128 v18, v[116:119]
	s_waitcnt vmcnt(14)
	ds_write_b128 v17, v[120:123]
	s_and_saveexec_b64 s[10:11], vcc
	s_cbranch_execz .LBB0_734
	v_subrev_u32_e32 v174, 32, v8
	v_lshlrev_b64 v[16:17], 4, v[174:175]
	v_lshl_add_u64 v[18:19], s[24:25], 0, v[16:17]
	v_lshl_add_u64 v[16:17], s[28:29], 0, v[16:17]
	global_store_dwordx4 v[18:19], v[116:119], off nt
	global_store_dwordx4 v[16:17], v[120:123], off nt

.Lrs_item:
	s_mov_b64 s[10:11], s[0:1]
	s_load_dwordx4 s[24:27], s[10:11], 0xb8
	s_load_dwordx2 s[28:29], s[10:11], 0xd0
	s_mov_b32 s30, s74
	s_waitcnt vmcnt(7)
	v_mov_b32_e32 v0, v236
	s_add_i32 s4, s81, 0xfffffcfa
	s_lshl_b32 s4, s4, 3
	s_waitcnt vmcnt(0)
	v_and_b32_e32 v29, 63, v0
	v_ashrrev_i32_e32 v0, 6, v0
	v_add_u32_e32 v28, s4, v0
	v_cmp_gt_i32_e32 vcc, s73, v28
	s_and_saveexec_b64 s[34:35], vcc
	s_cbranch_execz .LBB0_966
	s_load_dwordx4 s[20:23], s[10:11], 0x98
	s_lshl_b32 s10, s30, 12
	s_ashr_i32 s11, s10, 31
	s_lshl_b64 s[10:11], s[10:11], 2
	s_waitcnt lgkmcnt(0)
	s_add_u32 s4, s28, s10
	s_addc_u32 s10, s29, s11
	s_add_u32 s36, s4, 0xef8e000
	s_addc_u32 s37, s10, 0
	s_add_u32 s38, s4, 0xef96000
	s_addc_u32 s39, s10, 0
	s_lshl_b32 s10, s30, 10
	s_ashr_i32 s11, s10, 31
	s_lshl_b64 s[10:11], s[10:11], 2
	s_add_u32 s12, s22, s10
	s_addc_u32 s13, s23, s11
	s_add_u32 s10, s20, s10
	v_lshlrev_b32_e32 v30, 6, v29
	s_addc_u32 s11, s21, s11
	global_load_dwordx4 v[0:3], v30, s[12:13] offset:48
	global_load_dwordx4 v[8:11], v30, s[12:13] offset:32
	global_load_dwordx4 v[16:19], v30, s[12:13] offset:16
	global_load_dwordx4 v[24:27], v30, s[12:13]
	global_load_dwordx4 v[4:7], v30, s[10:11] offset:48
	global_load_dwordx4 v[12:15], v30, s[10:11] offset:32
	global_load_dwordx4 v[20:23], v30, s[10:11] offset:16
	s_nop 0
	global_load_dwordx4 v[30:33], v30, s[10:11]
	s_ashr_i32 s31, s30, 31
	s_lshl_b64 s[16:17], s[30:31], 23
	s_add_u32 s22, s28, s16
	s_addc_u32 s23, s29, s17
	v_lshlrev_b32_e32 v174, 5, v29
	s_mov_b64 s[40:41], 0
	s_waitcnt vmcnt(0)
	v_div_scale_f32 v34, s[10:11], v30, v30, v24
	v_rcp_f32_e32 v35, v34
	s_nop 0
	v_fma_f32 v36, -v34, v35, 1.0
	v_fmac_f32_e32 v35, v36, v35
	v_div_scale_f32 v36, vcc, v24, v30, v24
	v_mul_f32_e32 v37, v36, v35
	v_fma_f32 v38, -v34, v37, v36
	v_fmac_f32_e32 v37, v38, v35
	v_fma_f32 v34, -v34, v37, v36
	v_div_fmas_f32 v34, v34, v35, v37
	v_div_fixup_f32 v24, v34, v30, v24
	v_div_scale_f32 v30, s[10:11], v31, v31, v25
	v_rcp_f32_e32 v34, v30
	s_nop 0
	v_fma_f32 v35, -v30, v34, 1.0
	v_fmac_f32_e32 v34, v35, v34
	v_div_scale_f32 v35, vcc, v25, v31, v25
	v_mul_f32_e32 v36, v35, v34
	v_fma_f32 v37, -v30, v36, v35
	v_fmac_f32_e32 v36, v37, v34
	v_fma_f32 v30, -v30, v36, v35
	v_div_fmas_f32 v30, v30, v34, v36
	v_div_fixup_f32 v25, v30, v31, v25
	v_div_scale_f32 v30, s[10:11], v32, v32, v26
	v_rcp_f32_e32 v31, v30
	s_nop 0
	v_fma_f32 v34, -v30, v31, 1.0
	v_fmac_f32_e32 v31, v34, v31
	v_div_scale_f32 v34, vcc, v26, v32, v26
	v_mul_f32_e32 v35, v34, v31
	v_fma_f32 v36, -v30, v35, v34
	v_fmac_f32_e32 v35, v36, v31
	v_fma_f32 v30, -v30, v35, v34
	v_div_fmas_f32 v30, v30, v31, v35
	v_div_fixup_f32 v26, v30, v32, v26
	v_div_scale_f32 v30, s[10:11], v33, v33, v27
	v_rcp_f32_e32 v31, v30
	s_nop 0
	v_fma_f32 v32, -v30, v31, 1.0
	v_fmac_f32_e32 v31, v32, v31
	v_div_scale_f32 v32, vcc, v27, v33, v27
	v_mul_f32_e32 v34, v32, v31
	v_fma_f32 v35, -v30, v34, v32
	v_fmac_f32_e32 v34, v35, v31
	v_fma_f32 v30, -v30, v34, v32
	v_div_fmas_f32 v30, v30, v31, v34
	v_div_fixup_f32 v27, v30, v33, v27
	v_div_scale_f32 v30, s[10:11], v20, v20, v16
	v_rcp_f32_e32 v31, v30
	s_nop 0
	v_fma_f32 v32, -v30, v31, 1.0
	v_fmac_f32_e32 v31, v32, v31
	v_div_scale_f32 v32, vcc, v16, v20, v16
	v_mul_f32_e32 v33, v32, v31
	v_fma_f32 v34, -v30, v33, v32
	v_fmac_f32_e32 v33, v34, v31
	v_fma_f32 v30, -v30, v33, v32
	v_div_fmas_f32 v30, v30, v31, v33
	v_div_fixup_f32 v16, v30, v20, v16
	v_div_scale_f32 v20, s[10:11], v21, v21, v17
	v_rcp_f32_e32 v30, v20
	s_nop 0
	v_fma_f32 v31, -v20, v30, 1.0
	v_fmac_f32_e32 v30, v31, v30
	v_div_scale_f32 v31, vcc, v17, v21, v17
	v_mul_f32_e32 v32, v31, v30
	v_fma_f32 v33, -v20, v32, v31
	v_fmac_f32_e32 v32, v33, v30
	v_fma_f32 v20, -v20, v32, v31
	v_div_fmas_f32 v20, v20, v30, v32
	v_div_fixup_f32 v17, v20, v21, v17
	v_div_scale_f32 v20, s[10:11], v22, v22, v18
	v_rcp_f32_e32 v21, v20
	s_nop 0
	v_fma_f32 v30, -v20, v21, 1.0
	v_fmac_f32_e32 v21, v30, v21
	v_div_scale_f32 v30, vcc, v18, v22, v18
	v_mul_f32_e32 v31, v30, v21
	v_fma_f32 v32, -v20, v31, v30
	v_fmac_f32_e32 v31, v32, v21
	v_fma_f32 v20, -v20, v31, v30
	v_div_fmas_f32 v20, v20, v21, v31
	v_div_fixup_f32 v18, v20, v22, v18
	v_div_scale_f32 v20, s[10:11], v23, v23, v19
	v_rcp_f32_e32 v21, v20
	s_nop 0
	v_fma_f32 v22, -v20, v21, 1.0
	v_fmac_f32_e32 v21, v22, v21
	v_div_scale_f32 v22, vcc, v19, v23, v19
	v_mul_f32_e32 v30, v22, v21
	v_fma_f32 v31, -v20, v30, v22
	v_fmac_f32_e32 v30, v31, v21
	v_fma_f32 v20, -v20, v30, v22
	v_div_fmas_f32 v20, v20, v21, v30
	v_div_fixup_f32 v19, v20, v23, v19
	v_div_scale_f32 v20, s[10:11], v12, v12, v8
	v_rcp_f32_e32 v21, v20
	s_nop 0
	v_fma_f32 v22, -v20, v21, 1.0
	v_fmac_f32_e32 v21, v22, v21
	v_div_scale_f32 v22, vcc, v8, v12, v8
	v_mul_f32_e32 v23, v22, v21
	v_fma_f32 v30, -v20, v23, v22
	v_fmac_f32_e32 v23, v30, v21
	v_fma_f32 v20, -v20, v23, v22
	v_div_fmas_f32 v20, v20, v21, v23
	v_div_fixup_f32 v20, v20, v12, v8
	v_div_scale_f32 v8, s[10:11], v13, v13, v9
	v_rcp_f32_e32 v12, v8
	s_nop 0
	v_fma_f32 v21, -v8, v12, 1.0
	v_fmac_f32_e32 v12, v21, v12
	v_div_scale_f32 v21, vcc, v9, v13, v9
	v_mul_f32_e32 v22, v21, v12
	v_fma_f32 v23, -v8, v22, v21
	v_fmac_f32_e32 v22, v23, v12
	v_fma_f32 v8, -v8, v22, v21
	v_div_fmas_f32 v8, v8, v12, v22
	v_div_fixup_f32 v21, v8, v13, v9
	v_div_scale_f32 v8, s[10:11], v14, v14, v10
	v_rcp_f32_e32 v9, v8
	s_nop 0
	v_fma_f32 v12, -v8, v9, 1.0
	v_fmac_f32_e32 v9, v12, v9
	v_div_scale_f32 v12, vcc, v10, v14, v10
	v_mul_f32_e32 v13, v12, v9
	v_fma_f32 v22, -v8, v13, v12
	v_fmac_f32_e32 v13, v22, v9
	v_fma_f32 v8, -v8, v13, v12
	v_div_fmas_f32 v8, v8, v9, v13
	v_div_fixup_f32 v22, v8, v14, v10
	v_div_scale_f32 v8, s[10:11], v15, v15, v11
	v_rcp_f32_e32 v9, v8
	v_mov_b32_e32 v14, v28
	v_fma_f32 v10, -v8, v9, 1.0
	v_fmac_f32_e32 v9, v10, v9
	v_div_scale_f32 v10, vcc, v11, v15, v11
	v_mul_f32_e32 v12, v10, v9
	v_fma_f32 v13, -v8, v12, v10
	v_fmac_f32_e32 v12, v13, v9
	v_fma_f32 v8, -v8, v12, v10
	v_div_fmas_f32 v8, v8, v9, v12
	v_div_fixup_f32 v23, v8, v15, v11
	v_div_scale_f32 v8, s[10:11], v4, v4, v0
	v_rcp_f32_e32 v9, v8
	s_nop 0
	v_fma_f32 v10, -v8, v9, 1.0
	v_fmac_f32_e32 v9, v10, v9
	v_div_scale_f32 v10, vcc, v0, v4, v0
	v_mul_f32_e32 v11, v10, v9
	v_fma_f32 v12, -v8, v11, v10
	v_fmac_f32_e32 v11, v12, v9
	v_fma_f32 v8, -v8, v11, v10
	v_div_fmas_f32 v8, v8, v9, v11
	v_div_fixup_f32 v30, v8, v4, v0
	v_div_scale_f32 v0, s[10:11], v5, v5, v1
	v_rcp_f32_e32 v4, v0
	s_nop 0
	v_fma_f32 v8, -v0, v4, 1.0
	v_fmac_f32_e32 v4, v8, v4
	v_div_scale_f32 v8, vcc, v1, v5, v1
	v_mul_f32_e32 v9, v8, v4
	v_fma_f32 v10, -v0, v9, v8
	v_fmac_f32_e32 v9, v10, v4
	v_fma_f32 v0, -v0, v9, v8
	v_div_fmas_f32 v0, v0, v4, v9
	v_div_fixup_f32 v31, v0, v5, v1
	v_div_scale_f32 v0, s[10:11], v6, v6, v2
	v_rcp_f32_e32 v1, v0
	s_nop 0
	v_fma_f32 v4, -v0, v1, 1.0
	v_fmac_f32_e32 v1, v4, v1
	v_div_scale_f32 v4, vcc, v2, v6, v2
	v_mul_f32_e32 v5, v4, v1
	v_fma_f32 v8, -v0, v5, v4
	v_fmac_f32_e32 v5, v8, v1
	v_fma_f32 v0, -v0, v5, v4
	v_div_fmas_f32 v0, v0, v1, v5
	v_div_fixup_f32 v32, v0, v6, v2
	v_div_scale_f32 v0, s[10:11], v7, v7, v3
	v_rcp_f32_e32 v1, v0
	s_mov_b64 s[10:11], 0xa00000
	v_fma_f32 v2, -v0, v1, 1.0
	v_fmac_f32_e32 v1, v2, v1
	v_div_scale_f32 v2, vcc, v3, v7, v3
	v_mul_f32_e32 v4, v2, v1
	v_fma_f32 v5, -v0, v4, v2
	v_fmac_f32_e32 v4, v5, v1
	v_fma_f32 v0, -v0, v4, v2
	v_div_fmas_f32 v0, v0, v1, v4
	v_div_fixup_f32 v33, v0, v7, v3
	v_lshl_add_u64 v[0:1], s[22:23], 0, v[174:175]
	v_lshl_add_u64 v[12:13], v[0:1], 0, s[10:11]
	v_and_b32_e32 v0, 64, v237
	v_add_u32_e32 v0, 64, v0
	v_xor_b32_e32 v1, 1, v237
	v_cmp_lt_i32_e32 vcc, v1, v0
	s_nop 1
	v_cndmask_b32_e32 v1, v237, v1, vcc
	v_lshlrev_b32_e32 v34, 2, v1
	v_xor_b32_e32 v1, 2, v237
	v_cmp_lt_i32_e32 vcc, v1, v0
	s_nop 1
	v_cndmask_b32_e32 v1, v237, v1, vcc
	v_lshlrev_b32_e32 v35, 2, v1
	v_xor_b32_e32 v1, 4, v237
	v_cmp_lt_i32_e32 vcc, v1, v0
	s_nop 1
	v_cndmask_b32_e32 v1, v237, v1, vcc
	v_lshlrev_b32_e32 v36, 2, v1
	v_xor_b32_e32 v1, 8, v237
	v_cmp_lt_i32_e32 vcc, v1, v0
	s_nop 1
	v_cndmask_b32_e32 v1, v237, v1, vcc
	v_lshlrev_b32_e32 v37, 2, v1
	v_xor_b32_e32 v1, 16, v237
	v_cmp_lt_i32_e32 vcc, v1, v0
	s_nop 1
	v_cndmask_b32_e32 v1, v237, v1, vcc
	v_lshlrev_b32_e32 v38, 2, v1
	v_xor_b32_e32 v1, 32, v237
	v_cmp_lt_i32_e32 vcc, v1, v0
	s_nop 1
	v_cndmask_b32_e32 v0, v237, v1, vcc
	v_lshlrev_b32_e32 v39, 2, v0
	v_cmp_eq_u32_e32 vcc, 0, v29
	s_branch .LBB0_963

.Lrs_done:
	s_branch .LBB0_761

.LBB0_960:
.LBB0_974:
	s_mov_b64 s[10:11], s[0:1]
	s_waitcnt vmcnt(0)
	s_waitcnt lgkmcnt(0)
	s_barrier
	s_mov_b64 s[22:23], exec
	v_readlane_b32 s12, v254, 0
	v_readlane_b32 s13, v254, 1
	s_and_b64 s[12:13], s[22:23], s[12:13]
	s_mov_b64 exec, s[12:13]
	s_cbranch_execz .LBB0_1026
	s_load_dwordx2 s[24:25], s[10:11], 0xd0
	v_readlane_b32 s10, v255, 48
	s_getreg_b32 s4, hwreg(HW_REG_XCC_ID, 0, 4)
	s_waitcnt vmcnt(0) expcnt(0) lgkmcnt(0)
	v_mov_b32_e32 v0, s10
	ds_read_b32 v2, v0
	v_readlane_b32 s10, v255, 49
	s_and_b32 s4, s4, 15
	s_waitcnt lgkmcnt(0)
	v_cmp_ne_u32_e32 vcc, 0, v2
	v_mov_b32_e32 v0, s10
	ds_read_b32 v0, v0
	s_cbranch_vccnz .LBB0_990
	s_add_u32 s10, s24, 0xf02e200
	s_addc_u32 s11, s25, 0
	s_add_u32 s12, s24, 0xf02e400
	s_addc_u32 s13, s25, 0
	s_add_u32 s26, s24, 0xf02e500
	s_addc_u32 s27, s25, 0
	s_add_u32 s28, s24, 0xf02e600
	s_addc_u32 s29, s25, 0
	s_add_u32 s30, s24, 0xf02e700
	s_addc_u32 s31, s25, 0
	s_add_u32 s34, s24, 0xf02e800
	s_addc_u32 s35, s25, 0
	s_add_u32 s36, s24, 0xf02e900
	s_addc_u32 s37, s25, 0
	s_add_u32 s38, s24, 0xf02ea00
	s_addc_u32 s39, s25, 0
	s_add_u32 s40, s24, 0xf02eb00
	s_addc_u32 s41, s25, 0
	s_add_u32 s42, s24, 0xf02ec00
	s_addc_u32 s43, s25, 0
	s_add_u32 s44, s24, 0xf02ed00
	s_addc_u32 s45, s25, 0
	s_add_u32 s46, s24, 0xf02ee00
	s_addc_u32 s47, s25, 0
	s_add_u32 s48, s24, 0xf02ef00
	s_addc_u32 s49, s25, 0
	s_add_u32 s16, s24, 0xf02f000
	s_addc_u32 s17, s25, 0
	s_add_u32 s50, s24, 0xf02f100
	s_addc_u32 s51, s25, 0
	s_add_u32 s54, s24, 0xf02f200
	s_addc_u32 s55, s25, 0
	s_add_u32 s58, s24, 0xf02f300
	s_addc_u32 s59, s25, 0
	s_mov_b32 s75, 1
	s_branch .LBB0_978
